# NAT latent attention: the 32 relative-position-bias LDS reads of a tile issued as one batch (one wait) instead of 32 serialized round trips
# speedup vs baseline: 1.0413x; 1.0103x over previous
.LBB0_270:
	s_barrier
	ds_write_b128 v126, v[32:35]
	ds_write_b128 v127, v[44:47]
	ds_write_b16 v122, v40 offset:8192
	ds_write_b16_d16_hi v123, v40 offset:8328
	ds_write_b16 v122, v41 offset:8464
	ds_write_b16_d16_hi v123, v41 offset:8600
	ds_write_b16 v122, v42 offset:8736
	ds_write_b16_d16_hi v123, v42 offset:8872
	ds_write_b16 v122, v43 offset:9008
	ds_write_b16_d16_hi v123, v43 offset:9144
	ds_write_b16 v122, v36 offset:9280
	ds_write_b16_d16_hi v123, v36 offset:9416
	ds_write_b16 v122, v37 offset:9552
	ds_write_b16_d16_hi v123, v37 offset:9688
	ds_write_b16 v122, v38 offset:9824
	ds_write_b16_d16_hi v123, v38 offset:9960
	ds_write_b16 v122, v39 offset:10096
	ds_write_b16_d16_hi v123, v39 offset:10232
	s_waitcnt lgkmcnt(0)
	s_barrier
	ds_read_b128 v[32:35], v138
	ds_read_b128 v[36:39], v138 offset:4096
	s_waitcnt lgkmcnt(1)
	v_mfma_f32_32x32x16_bf16 v[48:63], v[32:35], v[64:67], 0
	ds_read_b128 v[146:149], v139
	ds_read_b128 v[150:153], v139 offset:4096
	s_add_i32 s40, s33, s44
	v_cmp_ge_u32_e32 vcc, s40, v115
	v_cmp_lt_u32_e64 s[40:41], s40, v120
	s_and_b64 s[96:97], vcc, s[40:41]
	s_andn2_b64 vcc, exec, s[4:5]
	s_waitcnt lgkmcnt(2)
	v_mfma_f32_32x32x16_bf16 v[32:47], v[36:39], v[64:67], 0
	s_waitcnt lgkmcnt(1)
	v_mfma_f32_32x32x16_bf16 v[48:63], v[146:149], v[68:71], v[48:63]
	s_waitcnt lgkmcnt(0)
	v_mfma_f32_32x32x16_bf16 v[32:47], v[150:153], v[68:71], v[32:47]
	ds_read_b128 v[146:149], v140
	ds_read_b128 v[150:153], v140 offset:4096
	s_waitcnt lgkmcnt(1)
	v_mfma_f32_32x32x16_bf16 v[48:63], v[146:149], v[72:75], v[48:63]
	s_waitcnt lgkmcnt(0)
	v_mfma_f32_32x32x16_bf16 v[32:47], v[150:153], v[72:75], v[32:47]
	ds_read_b128 v[146:149], v141
	ds_read_b128 v[150:153], v141 offset:4096
	s_waitcnt lgkmcnt(1)
	v_mfma_f32_32x32x16_bf16 v[48:63], v[146:149], v[76:79], v[48:63]
	s_waitcnt lgkmcnt(0)
	v_mfma_f32_32x32x16_bf16 v[32:47], v[150:153], v[76:79], v[32:47]
	s_nop 9
	v_mul_f32_e32 v147, 0x3e000000, v48
	v_cndmask_b32_e64 v48, 0, 1, s[4:5]
	v_cmp_ne_u32_e64 s[40:41], 1, v48
	s_cbranch_vccnz .LBB0_302
	s_movk_i32 s4, 0x1d0
	v_subrev_u32_e32 v190, 59, v124
	v_subrev_u32_e32 v191, 57, v124
	v_subrev_u32_e32 v192, 51, v124
	v_subrev_u32_e32 v193, 49, v124
	v_subrev_u32_e32 v194, 43, v124
	v_subrev_u32_e32 v195, 41, v124
	v_subrev_u32_e32 v196, 35, v124
	v_subrev_u32_e32 v197, 33, v124
	v_subrev_u32_e32 v198, 27, v124
	v_subrev_u32_e32 v199, 25, v124
	v_subrev_u32_e32 v200, 19, v124
	v_subrev_u32_e32 v201, 17, v124
	v_subrev_u32_e32 v202, 11, v124
	v_subrev_u32_e32 v203, 9, v124
	v_subrev_u32_e32 v204, 3, v124
	v_subrev_u32_e32 v205, 1, v124
	v_subrev_u32_e32 v206, 58, v124
	v_subrev_u32_e32 v207, 56, v124
	v_subrev_u32_e32 v208, 50, v124
	v_subrev_u32_e32 v209, 48, v124
	v_subrev_u32_e32 v210, 42, v124
	v_subrev_u32_e32 v211, 40, v124
	v_subrev_u32_e32 v212, 34, v124
	v_subrev_u32_e32 v213, 32, v124
	v_subrev_u32_e32 v214, 26, v124
	v_subrev_u32_e32 v215, 24, v124
	v_subrev_u32_e32 v216, 18, v124
	v_subrev_u32_e32 v217, 16, v124
	v_subrev_u32_e32 v218, 10, v124
	v_subrev_u32_e32 v219, 8, v124
	v_subrev_u32_e32 v220, 2, v124
	v_mov_b32_e32 v221, v124
	v_med3_i32 v190, v190, 0, s4
	v_med3_i32 v191, v191, 0, s4
	v_med3_i32 v192, v192, 0, s4
	v_med3_i32 v193, v193, 0, s4
	v_med3_i32 v194, v194, 0, s4
	v_med3_i32 v195, v195, 0, s4
	v_med3_i32 v196, v196, 0, s4
	v_med3_i32 v197, v197, 0, s4
	v_med3_i32 v198, v198, 0, s4
	v_med3_i32 v199, v199, 0, s4
	v_med3_i32 v200, v200, 0, s4
	v_med3_i32 v201, v201, 0, s4
	v_med3_i32 v202, v202, 0, s4
	v_med3_i32 v203, v203, 0, s4
	v_med3_i32 v204, v204, 0, s4
	v_med3_i32 v205, v205, 0, s4
	v_med3_i32 v206, v206, 0, s4
	v_med3_i32 v207, v207, 0, s4
	v_med3_i32 v208, v208, 0, s4
	v_med3_i32 v209, v209, 0, s4
	v_med3_i32 v210, v210, 0, s4
	v_med3_i32 v211, v211, 0, s4
	v_med3_i32 v212, v212, 0, s4
	v_med3_i32 v213, v213, 0, s4
	v_med3_i32 v214, v214, 0, s4
	v_med3_i32 v215, v215, 0, s4
	v_med3_i32 v216, v216, 0, s4
	v_med3_i32 v217, v217, 0, s4
	v_med3_i32 v218, v218, 0, s4
	v_med3_i32 v219, v219, 0, s4
	v_med3_i32 v220, v220, 0, s4
	v_med3_i32 v221, v221, 0, s4
	v_lshl_add_u32 v190, v190, 2, s78
	v_lshl_add_u32 v191, v191, 2, s78
	v_lshl_add_u32 v192, v192, 2, s78
	v_lshl_add_u32 v193, v193, 2, s78
	v_lshl_add_u32 v194, v194, 2, s78
	v_lshl_add_u32 v195, v195, 2, s78
	v_lshl_add_u32 v196, v196, 2, s78
	v_lshl_add_u32 v197, v197, 2, s78
	v_lshl_add_u32 v198, v198, 2, s78
	v_lshl_add_u32 v199, v199, 2, s78
	v_lshl_add_u32 v200, v200, 2, s78
	v_lshl_add_u32 v201, v201, 2, s78
	v_lshl_add_u32 v202, v202, 2, s78
	v_lshl_add_u32 v203, v203, 2, s78
	v_lshl_add_u32 v204, v204, 2, s78
	v_lshl_add_u32 v205, v205, 2, s78
	v_lshl_add_u32 v206, v206, 2, s78
	v_lshl_add_u32 v207, v207, 2, s78
	v_lshl_add_u32 v208, v208, 2, s78
	v_lshl_add_u32 v209, v209, 2, s78
	v_lshl_add_u32 v210, v210, 2, s78
	v_lshl_add_u32 v211, v211, 2, s78
	v_lshl_add_u32 v212, v212, 2, s78
	v_lshl_add_u32 v213, v213, 2, s78
	v_lshl_add_u32 v214, v214, 2, s78
	v_lshl_add_u32 v215, v215, 2, s78
	v_lshl_add_u32 v216, v216, 2, s78
	v_lshl_add_u32 v217, v217, 2, s78
	v_lshl_add_u32 v218, v218, 2, s78
	v_lshl_add_u32 v219, v219, 2, s78
	v_lshl_add_u32 v220, v220, 2, s78
	v_lshl_add_u32 v221, v221, 2, s78
	ds_read_b32 v190, v190 offset:16896
	ds_read_b32 v191, v191 offset:16896
	ds_read_b32 v192, v192 offset:16896
	ds_read_b32 v193, v193 offset:16896
	ds_read_b32 v194, v194 offset:16896
	ds_read_b32 v195, v195 offset:16896
	ds_read_b32 v196, v196 offset:16896
	ds_read_b32 v197, v197 offset:16896
	ds_read_b32 v198, v198 offset:16896
	ds_read_b32 v199, v199 offset:16896
	ds_read_b32 v200, v200 offset:16896
	ds_read_b32 v201, v201 offset:16896
	ds_read_b32 v202, v202 offset:16896
	ds_read_b32 v203, v203 offset:16896
	ds_read_b32 v204, v204 offset:16896
	ds_read_b32 v205, v205 offset:16896
	ds_read_b32 v206, v206 offset:16896
	ds_read_b32 v207, v207 offset:16896
	ds_read_b32 v208, v208 offset:16896
	ds_read_b32 v209, v209 offset:16896
	ds_read_b32 v210, v210 offset:16896
	ds_read_b32 v211, v211 offset:16896
	ds_read_b32 v212, v212 offset:16896
	ds_read_b32 v213, v213 offset:16896
	ds_read_b32 v214, v214 offset:16896
	ds_read_b32 v215, v215 offset:16896
	ds_read_b32 v216, v216 offset:16896
	ds_read_b32 v217, v217 offset:16896
	ds_read_b32 v218, v218 offset:16896
	ds_read_b32 v219, v219 offset:16896
	ds_read_b32 v220, v220 offset:16896
	ds_read_b32 v221, v221 offset:16896
	s_waitcnt lgkmcnt(0)
	s_and_b64 vcc, s[96:97], s[64:65]
	v_add_f32_e32 v48, v147, v190
	v_cndmask_b32_e32 v147, v169, v48, vcc
	s_and_b64 vcc, exec, s[40:41]
	v_mul_f32_e32 v146, 0x3e000000, v49
	s_cbranch_vccz .LBB0_303

.LBB0_273:
	s_and_b64 vcc, s[96:97], s[68:69]
	v_add_f32_e32 v48, v119, v191
	v_cndmask_b32_e32 v119, v169, v48, vcc
	s_and_b64 vcc, exec, s[40:41]
	v_mul_f32_e32 v145, 0x3e000000, v51
	s_cbranch_vccz .LBB0_305

.LBB0_275:
	s_and_b64 vcc, s[96:97], s[72:73]
	v_add_f32_e32 v48, v51, v192
	v_cndmask_b32_e32 v51, v169, v48, vcc
	s_and_b64 vcc, exec, s[40:41]
	v_mul_f32_e32 v52, 0x3e000000, v53
	s_cbranch_vccz .LBB0_307

.LBB0_277:
	v_readlane_b32 s4, v254, 45
	v_readlane_b32 s5, v254, 46
	s_and_b64 vcc, s[96:97], s[4:5]
	v_add_f32_e32 v48, v48, v193
	v_cndmask_b32_e32 v48, v169, v48, vcc
	s_and_b64 vcc, exec, s[40:41]
	v_mul_f32_e32 v50, 0x3e000000, v55
	s_cbranch_vccz .LBB0_309

.LBB0_279:
	v_readlane_b32 s4, v254, 49
	v_readlane_b32 s5, v254, 50
	v_readlane_b32 vcc_lo, v254, 51
	s_and_b64 s[4:5], s[96:97], s[4:5]
	v_readlane_b32 vcc_hi, v254, 52
	s_and_b64 vcc, s[4:5], vcc
	v_add_f32_e32 v49, v49, v194
	v_cndmask_b32_e32 v49, v169, v49, vcc
	s_and_b64 vcc, exec, s[40:41]
	v_mul_f32_e32 v53, 0x3e000000, v57
	s_cbranch_vccz .LBB0_311

.LBB0_281:
	v_readlane_b32 s4, v254, 57
	v_readlane_b32 s5, v254, 58
	v_readlane_b32 vcc_lo, v255, 26
	s_and_b64 s[4:5], s[96:97], s[4:5]
	v_readlane_b32 vcc_hi, v255, 27
	s_and_b64 vcc, s[4:5], vcc
	v_add_f32_e32 v54, v54, v195
	v_cndmask_b32_e32 v54, v169, v54, vcc
	s_and_b64 vcc, exec, s[40:41]
	v_mul_f32_e32 v55, 0x3e000000, v59
	s_cbranch_vccz .LBB0_313

.LBB0_283:
	v_readlane_b32 s4, v255, 32
	v_readlane_b32 s5, v255, 33
	v_readlane_b32 vcc_lo, v255, 34
	s_and_b64 s[4:5], s[96:97], s[4:5]
	v_readlane_b32 vcc_hi, v255, 35
	s_and_b64 vcc, s[4:5], vcc
	v_add_f32_e32 v56, v56, v196
	v_cndmask_b32_e32 v56, v169, v56, vcc
	s_and_b64 vcc, exec, s[40:41]
	v_mul_f32_e32 v57, 0x3e000000, v61
	s_cbranch_vccz .LBB0_315

.LBB0_285:
	v_readlane_b32 s4, v255, 40
	v_readlane_b32 s5, v255, 41
	v_readlane_b32 vcc_lo, v255, 42
	s_and_b64 s[4:5], s[96:97], s[4:5]
	v_readlane_b32 vcc_hi, v255, 43
	s_and_b64 vcc, s[4:5], vcc
	v_add_f32_e32 v58, v58, v197
	v_cndmask_b32_e32 v58, v169, v58, vcc
	s_and_b64 vcc, exec, s[40:41]
	v_mul_f32_e32 v59, 0x3e000000, v63
	s_cbranch_vccz .LBB0_317

.LBB0_287:
	v_readlane_b32 s4, v255, 48
	v_readlane_b32 s5, v255, 49
	v_readlane_b32 vcc_lo, v255, 50
	s_and_b64 s[4:5], s[96:97], s[4:5]
	v_readlane_b32 vcc_hi, v255, 51
	s_and_b64 vcc, s[4:5], vcc
	v_add_f32_e32 v32, v60, v198
	v_cndmask_b32_e32 v60, v169, v32, vcc
	s_and_b64 vcc, exec, s[40:41]
	v_mul_f32_e32 v61, 0x3e000000, v33
	s_cbranch_vccz .LBB0_319

.LBB0_289:
	v_readlane_b32 s4, v255, 56
	v_readlane_b32 s5, v255, 57
	v_readlane_b32 vcc_lo, v255, 58
	s_and_b64 s[4:5], s[96:97], s[4:5]
	v_readlane_b32 vcc_hi, v255, 59
	s_and_b64 vcc, s[4:5], vcc
	v_add_f32_e32 v32, v62, v199
	v_cndmask_b32_e32 v62, v169, v32, vcc
	s_and_b64 vcc, exec, s[40:41]
	v_mul_f32_e32 v150, 0x3e000000, v35
	s_cbranch_vccz .LBB0_321

.LBB0_291:
	s_and_b64 s[4:5], s[96:97], s[6:7]
	s_and_b64 vcc, s[4:5], s[8:9]
	v_add_f32_e32 v32, v151, v200
	v_cndmask_b32_e32 v151, v169, v32, vcc
	s_and_b64 vcc, exec, s[40:41]
	v_mul_f32_e32 v153, 0x3e000000, v37
	s_cbranch_vccz .LBB0_323

.LBB0_293:
	s_and_b64 s[4:5], s[96:97], s[14:15]
	s_and_b64 vcc, s[4:5], s[16:17]
	v_add_f32_e32 v32, v149, v201
	v_cndmask_b32_e32 v149, v169, v32, vcc
	s_and_b64 vcc, exec, s[40:41]
	v_mul_f32_e32 v152, 0x3e000000, v39
	s_cbranch_vccz .LBB0_325

.LBB0_295:
	s_and_b64 vcc, s[96:97], s[22:23]
	v_add_f32_e32 v32, v63, v202
	v_cndmask_b32_e32 v63, v169, v32, vcc
	s_and_b64 vcc, exec, s[40:41]
	v_mul_f32_e32 v148, 0x3e000000, v41
	s_cbranch_vccz .LBB0_327

.LBB0_297:
	s_and_b64 vcc, s[96:97], s[26:27]
	v_add_f32_e32 v32, v41, v203
	v_cndmask_b32_e32 v41, v169, v32, vcc
	s_and_b64 vcc, exec, s[40:41]
	v_mul_f32_e32 v42, 0x3e000000, v43
	s_cbranch_vccz .LBB0_329

.LBB0_299:
	s_and_b64 vcc, s[96:97], s[30:31]
	v_add_f32_e32 v32, v39, v204
	v_cndmask_b32_e32 v39, v169, v32, vcc
	s_and_b64 vcc, exec, s[40:41]
	v_mul_f32_e32 v45, 0x3e000000, v45
	s_cbranch_vccz .LBB0_331

.LBB0_301:
	s_and_b64 vcc, s[96:97], s[0:1]
	v_add_f32_e32 v32, v46, v205
	v_cndmask_b32_e32 v46, v169, v32, vcc
	s_and_b64 vcc, exec, s[40:41]
	v_mul_f32_e32 v154, 0x3e000000, v47
	s_cbranch_vccz .LBB0_333
	s_branch .LBB0_334

.LBB0_303:
	s_and_b64 vcc, s[96:97], s[66:67]
	v_add_f32_e32 v48, v146, v206
	v_cndmask_b32_e32 v146, v169, v48, vcc
	s_and_b64 vcc, exec, s[40:41]
	v_mul_f32_e32 v119, 0x3e000000, v50
	s_cbranch_vccz .LBB0_273

.LBB0_305:
	s_and_b64 vcc, s[96:97], s[70:71]
	v_add_f32_e32 v48, v145, v207
	v_cndmask_b32_e32 v145, v169, v48, vcc
	s_and_b64 vcc, exec, s[40:41]
	v_mul_f32_e32 v51, 0x3e000000, v52
	s_cbranch_vccz .LBB0_275

.LBB0_307:
	s_and_b64 vcc, s[96:97], s[74:75]
	v_add_f32_e32 v48, v52, v208
	v_cndmask_b32_e32 v52, v169, v48, vcc
	s_and_b64 vcc, exec, s[40:41]
	v_mul_f32_e32 v48, 0x3e000000, v54
	s_cbranch_vccz .LBB0_277

.LBB0_309:
	v_readlane_b32 s4, v254, 47
	v_readlane_b32 s5, v254, 48
	s_and_b64 vcc, s[96:97], s[4:5]
	v_add_f32_e32 v49, v50, v209
	v_cndmask_b32_e32 v50, v169, v49, vcc
	s_and_b64 vcc, exec, s[40:41]
	v_mul_f32_e32 v49, 0x3e000000, v56
	s_cbranch_vccz .LBB0_279

.LBB0_311:
	v_readlane_b32 s4, v254, 53
	v_readlane_b32 s5, v254, 54
	v_readlane_b32 vcc_lo, v254, 55
	s_and_b64 s[4:5], s[96:97], s[4:5]
	v_readlane_b32 vcc_hi, v254, 56
	s_and_b64 vcc, s[4:5], vcc
	v_add_f32_e32 v53, v53, v210
	v_cndmask_b32_e32 v53, v169, v53, vcc
	s_and_b64 vcc, exec, s[40:41]
	v_mul_f32_e32 v54, 0x3e000000, v58
	s_cbranch_vccz .LBB0_281

.LBB0_313:
	v_readlane_b32 s4, v255, 28
	v_readlane_b32 s5, v255, 29
	v_readlane_b32 vcc_lo, v255, 30
	s_and_b64 s[4:5], s[96:97], s[4:5]
	v_readlane_b32 vcc_hi, v255, 31
	s_and_b64 vcc, s[4:5], vcc
	v_add_f32_e32 v55, v55, v211
	v_cndmask_b32_e32 v55, v169, v55, vcc
	s_and_b64 vcc, exec, s[40:41]
	v_mul_f32_e32 v56, 0x3e000000, v60
	s_cbranch_vccz .LBB0_283

.LBB0_315:
	v_readlane_b32 s4, v255, 36
	v_readlane_b32 s5, v255, 37
	v_readlane_b32 vcc_lo, v255, 38
	s_and_b64 s[4:5], s[96:97], s[4:5]
	v_readlane_b32 vcc_hi, v255, 39
	s_and_b64 vcc, s[4:5], vcc
	v_add_f32_e32 v57, v57, v212
	v_cndmask_b32_e32 v57, v169, v57, vcc
	s_and_b64 vcc, exec, s[40:41]
	v_mul_f32_e32 v58, 0x3e000000, v62
	s_cbranch_vccz .LBB0_285

.LBB0_317:
	v_readlane_b32 s4, v255, 44
	v_readlane_b32 s5, v255, 45
	v_readlane_b32 vcc_lo, v255, 46
	s_and_b64 s[4:5], s[96:97], s[4:5]
	v_readlane_b32 vcc_hi, v255, 47
	s_and_b64 vcc, s[4:5], vcc
	v_add_f32_e32 v59, v59, v213
	v_cndmask_b32_e32 v59, v169, v59, vcc
	s_and_b64 vcc, exec, s[40:41]
	v_mul_f32_e32 v60, 0x3e000000, v32
	s_cbranch_vccz .LBB0_287

.LBB0_319:
	v_readlane_b32 s4, v255, 52
	v_readlane_b32 s5, v255, 53
	v_readlane_b32 vcc_lo, v255, 54
	s_and_b64 s[4:5], s[96:97], s[4:5]
	v_readlane_b32 vcc_hi, v255, 55
	s_and_b64 vcc, s[4:5], vcc
	v_add_f32_e32 v32, v61, v214
	v_cndmask_b32_e32 v61, v169, v32, vcc
	s_and_b64 vcc, exec, s[40:41]
	v_mul_f32_e32 v62, 0x3e000000, v34
	s_cbranch_vccz .LBB0_289

.LBB0_321:
	v_readlane_b32 s4, v255, 60
	v_readlane_b32 s5, v255, 61
	v_readlane_b32 vcc_lo, v255, 62
	s_and_b64 s[4:5], s[96:97], s[4:5]
	v_readlane_b32 vcc_hi, v255, 63
	s_and_b64 vcc, s[4:5], vcc
	v_add_f32_e32 v32, v150, v215
	v_cndmask_b32_e32 v150, v169, v32, vcc
	s_and_b64 vcc, exec, s[40:41]
	v_mul_f32_e32 v151, 0x3e000000, v36
	s_cbranch_vccz .LBB0_291

.LBB0_323:
	s_and_b64 s[4:5], s[96:97], s[10:11]
	s_and_b64 vcc, s[4:5], s[12:13]
	v_add_f32_e32 v32, v153, v216
	v_cndmask_b32_e32 v153, v169, v32, vcc
	s_and_b64 vcc, exec, s[40:41]
	v_mul_f32_e32 v149, 0x3e000000, v38
	s_cbranch_vccz .LBB0_293

.LBB0_325:
	s_and_b64 s[4:5], s[96:97], s[18:19]
	s_and_b64 vcc, s[4:5], s[20:21]
	v_add_f32_e32 v32, v152, v217
	v_cndmask_b32_e32 v152, v169, v32, vcc
	s_and_b64 vcc, exec, s[40:41]
	v_mul_f32_e32 v63, 0x3e000000, v40
	s_cbranch_vccz .LBB0_295

.LBB0_327:
	s_and_b64 vcc, s[96:97], s[24:25]
	v_add_f32_e32 v32, v148, v218
	v_cndmask_b32_e32 v148, v169, v32, vcc
	s_and_b64 vcc, exec, s[40:41]
	v_mul_f32_e32 v41, 0x3e000000, v42
	s_cbranch_vccz .LBB0_297

.LBB0_329:
	s_and_b64 vcc, s[96:97], s[28:29]
	v_add_f32_e32 v32, v42, v219
	v_cndmask_b32_e32 v42, v169, v32, vcc
	s_and_b64 vcc, exec, s[40:41]
	v_mul_f32_e32 v39, 0x3e000000, v44
	s_cbranch_vccz .LBB0_299

.LBB0_331:
	s_and_b64 vcc, s[96:97], s[34:35]
	v_add_f32_e32 v32, v45, v220
	v_cndmask_b32_e32 v45, v169, v32, vcc
	s_and_b64 vcc, exec, s[40:41]
	v_mul_f32_e32 v46, 0x3e000000, v46
	s_cbranch_vccz .LBB0_301

.LBB0_333:
	s_and_b64 vcc, s[96:97], s[38:39]
	v_add_f32_e32 v32, v154, v221
	v_cndmask_b32_e32 v154, v169, v32, vcc
